# grid barrier: arrival ticket consumed without waiting for the early L1 invalidate (vmcnt(1))
# baseline (speedup 1.0000x reference)
; __device__ __forceinline__ int lane_id() { return (int)__builtin_amdgcn_mbcnt_hi(~0u, __builtin_amdgcn_mbcnt_lo(~0u, 0u)); }
; __device__ __forceinline__ unsigned xb_ld(unsigned* p)              { return __hip_atomic_load(p, __ATOMIC_RELAXED, __HIP_MEMORY_SCOPE_AGENT); }
; __device__ __forceinline__ unsigned xb_add(unsigned* p, unsigned v) { return __hip_atomic_fetch_add(p, v, __ATOMIC_RELAXED, __HIP_MEMORY_SCOPE_AGENT); }
; #define XB_SPIN(cond, bar) do { unsigned _sp = 0; while (cond) { __builtin_amdgcn_s_sleep(1); \
;     if ((++_sp & 255u) == 0u) { if (xb_ld(&(bar)[XB_TMO])) break; if (_sp > XB_SPIN_CAP) { atomicAdd(&(bar)[XB_TMO], 1u); break; } } } } while (0)
; __device__ __forceinline__ void xcd_barrier(const XcdBarrier& b) {
;     asm volatile("s_waitcnt vmcnt(0)" ::: "memory");
;     __syncthreads();
;     if (b.wid == 0 && lane_id() == 0) {
;         unsigned* bar = b.bar;
;         __builtin_amdgcn_s_waitcnt(0);
;         unsigned nloc = b.st[0], nx = b.st[1];
;         if (nloc == 0u) { xcd_barrier_complete(bar, b.x, nloc, nx); b.st[0] = nloc; b.st[1] = nx; }
;         const unsigned old = xb_add(&bar[XB_XSUB(b.x)], 1u);
;         const unsigned gen = old / nloc;
;         if (old + 1u == (gen + 1u) * nloc) {
;             __builtin_amdgcn_fence(__ATOMIC_RELEASE, "agent");
;             asm volatile("s_waitcnt vmcnt(0)" ::: "memory");
;             const unsigned og = xb_add(&bar[XB_TOP], 1u);
;             const unsigned tg = og / nx;
;             if (og + 1u == (tg + 1u) * nx) xb_add(&bar[XB_TOPGEN], 1u);
;             else XB_SPIN(xb_ld(&bar[XB_TOPGEN]) == tg, bar);
;             __builtin_amdgcn_fence(__ATOMIC_ACQUIRE, "agent");
;             xb_add(&bar[XB_XGEN(b.x)], 1u);
;             asm volatile("s_waitcnt vmcnt(0)" ::: "memory");
;         } else {
;             XB_SPIN(xb_ld(&bar[XB_XGEN(b.x)]) == gen, bar);
;             __builtin_amdgcn_fence(__ATOMIC_ACQUIRE, "agent");
;             asm volatile("s_waitcnt vmcnt(0)" ::: "memory");
;         }
.LBB0_59:
	s_lshl_b32 s6, s87, 8
	s_add_u32 s6, s88, s6
	s_addc_u32 s7, s89, 0
	v_mov_b32_e32 v1, 0x1000
	v_mov_b32_e32 v3, 1
	global_atomic_add v3, v1, v3, s[6:7] offset:1024 sc0
	buffer_inv sc1
	v_cvt_f32_u32_e32 v1, v2
	v_sub_u32_e32 v4, 0, v2
	v_rcp_iflag_f32_e32 v1, v1
	s_nop 0
	v_mul_f32_e32 v1, 0x4f7ffffe, v1
	v_cvt_u32_f32_e32 v1, v1
	v_mul_lo_u32 v4, v4, v1
	v_mul_hi_u32 v4, v1, v4
	v_add_u32_e32 v1, v1, v4
	s_waitcnt vmcnt(1)
	v_mul_hi_u32 v1, v3, v1
	v_mul_lo_u32 v4, v1, v2
	v_sub_u32_e32 v4, v3, v4
	v_add_u32_e32 v5, 1, v1
	v_cmp_ge_u32_e32 vcc, v4, v2
	v_add_u32_e32 v3, 1, v3
	s_nop 0
	v_cndmask_b32_e32 v1, v1, v5, vcc
	v_sub_u32_e32 v5, v4, v2
	v_cndmask_b32_e32 v4, v4, v5, vcc
	v_add_u32_e32 v5, 1, v1
	v_cmp_ge_u32_e32 vcc, v4, v2
	s_nop 1
	v_cndmask_b32_e32 v1, v1, v5, vcc
	v_mul_lo_u32 v4, v2, v1
	v_add_u32_e32 v2, v4, v2
	v_cmp_ne_u32_e32 vcc, v3, v2
	s_and_saveexec_b64 s[14:15], vcc
	s_xor_b64 s[14:15], exec, s[14:15]
	s_cbranch_execz .LBB0_73
	s_waitcnt lgkmcnt(0)
	v_mov_b32_e32 v0, 0x2000
	global_load_dword v0, v0, s[6:7] offset:1024 sc1
	s_add_u32 s20, s6, 0x2400
	s_addc_u32 s21, s7, 0
	s_waitcnt vmcnt(0)
	v_cmp_eq_u32_e32 vcc, v0, v1
	s_and_saveexec_b64 s[16:17], vcc
	s_cbranch_execz .LBB0_72
	s_add_u32 s18, s80, 0x10200
	s_addc_u32 s19, s81, 0
	s_mov_b32 s33, 1
	s_mov_b64 s[22:23], 0
	v_mov_b32_e32 v0, 0
	s_branch .LBB0_63

; __device__ __forceinline__ int lane_id() { return (int)__builtin_amdgcn_mbcnt_hi(~0u, __builtin_amdgcn_mbcnt_lo(~0u, 0u)); }
; __device__ __forceinline__ unsigned xb_ld(unsigned* p)              { return __hip_atomic_load(p, __ATOMIC_RELAXED, __HIP_MEMORY_SCOPE_AGENT); }
; __device__ __forceinline__ unsigned xb_add(unsigned* p, unsigned v) { return __hip_atomic_fetch_add(p, v, __ATOMIC_RELAXED, __HIP_MEMORY_SCOPE_AGENT); }
; #define XB_SPIN(cond, bar) do { unsigned _sp = 0; while (cond) { __builtin_amdgcn_s_sleep(1); \
;     if ((++_sp & 255u) == 0u) { if (xb_ld(&(bar)[XB_TMO])) break; if (_sp > XB_SPIN_CAP) { atomicAdd(&(bar)[XB_TMO], 1u); break; } } } } while (0)
; __device__ __forceinline__ void xcd_barrier(const XcdBarrier& b) {
;     asm volatile("s_waitcnt vmcnt(0)" ::: "memory");
;     __syncthreads();
;     if (b.wid == 0 && lane_id() == 0) {
;         unsigned* bar = b.bar;
;         __builtin_amdgcn_s_waitcnt(0);
;         unsigned nloc = b.st[0], nx = b.st[1];
;         if (nloc == 0u) { xcd_barrier_complete(bar, b.x, nloc, nx); b.st[0] = nloc; b.st[1] = nx; }
;         const unsigned old = xb_add(&bar[XB_XSUB(b.x)], 1u);
;         const unsigned gen = old / nloc;
;         if (old + 1u == (gen + 1u) * nloc) {
;             __builtin_amdgcn_fence(__ATOMIC_RELEASE, "agent");
;             asm volatile("s_waitcnt vmcnt(0)" ::: "memory");
;             const unsigned og = xb_add(&bar[XB_TOP], 1u);
;             const unsigned tg = og / nx;
;             if (og + 1u == (tg + 1u) * nx) xb_add(&bar[XB_TOPGEN], 1u);
;             else XB_SPIN(xb_ld(&bar[XB_TOPGEN]) == tg, bar);
;             __builtin_amdgcn_fence(__ATOMIC_ACQUIRE, "agent");
;             xb_add(&bar[XB_XGEN(b.x)], 1u);
;             asm volatile("s_waitcnt vmcnt(0)" ::: "memory");
;         } else {
;             XB_SPIN(xb_ld(&bar[XB_XGEN(b.x)]) == gen, bar);
;             __builtin_amdgcn_fence(__ATOMIC_ACQUIRE, "agent");
;             asm volatile("s_waitcnt vmcnt(0)" ::: "memory");
;         }
.LBB0_527:
	s_lshl_b32 s4, s87, 8
	s_add_u32 s4, s88, s4
	s_addc_u32 s5, s89, 0
	v_mov_b32_e32 v1, 0x1000
	v_mov_b32_e32 v3, 1
	global_atomic_add v3, v1, v3, s[4:5] offset:1024 sc0
	buffer_inv sc1
	v_cvt_f32_u32_e32 v1, v2
	v_sub_u32_e32 v4, 0, v2
	v_rcp_iflag_f32_e32 v1, v1
	s_nop 0
	v_mul_f32_e32 v1, 0x4f7ffffe, v1
	v_cvt_u32_f32_e32 v1, v1
	v_mul_lo_u32 v4, v4, v1
	v_mul_hi_u32 v4, v1, v4
	v_add_u32_e32 v1, v1, v4
	s_waitcnt vmcnt(1)
	v_mul_hi_u32 v1, v3, v1
	v_mul_lo_u32 v4, v1, v2
	v_sub_u32_e32 v4, v3, v4
	v_add_u32_e32 v5, 1, v1
	v_cmp_ge_u32_e32 vcc, v4, v2
	v_add_u32_e32 v3, 1, v3
	s_nop 0
	v_cndmask_b32_e32 v1, v1, v5, vcc
	v_sub_u32_e32 v5, v4, v2
	v_cndmask_b32_e32 v4, v4, v5, vcc
	v_add_u32_e32 v5, 1, v1
	v_cmp_ge_u32_e32 vcc, v4, v2
	s_nop 1
	v_cndmask_b32_e32 v1, v1, v5, vcc
	v_mul_lo_u32 v4, v2, v1
	v_add_u32_e32 v2, v4, v2
	v_cmp_ne_u32_e32 vcc, v3, v2
	s_and_saveexec_b64 s[6:7], vcc
	s_xor_b64 s[6:7], exec, s[6:7]
	s_cbranch_execz .LBB0_541
	s_waitcnt lgkmcnt(0)
	v_mov_b32_e32 v0, 0x2000
	global_load_dword v0, v0, s[4:5] offset:1024 sc1
	s_add_u32 s12, s4, 0x2400
	s_addc_u32 s13, s5, 0
	s_waitcnt vmcnt(0)
	v_cmp_eq_u32_e32 vcc, v0, v1
	s_and_saveexec_b64 s[8:9], vcc
	s_cbranch_execz .LBB0_540
	s_add_u32 s10, s80, 0x10200
	s_addc_u32 s11, s81, 0
	s_mov_b32 s24, 1
	s_mov_b64 s[14:15], 0
	v_mov_b32_e32 v0, 0
	s_branch .LBB0_531
